# out-proj to FF1 seam keeps the grid barrier for ordering but skips the L2 write-back when the placement check holds (all consumers of out-proj outputs until the next write-back are on the same XCD)
# baseline (speedup 1.0000x reference)
.LBB0_968:
	s_andn2_saveexec_b64 s[4:5], s[12:13]
	s_cbranch_execz .LBB0_988
	s_mov_b64 s[12:13], exec
	s_cmp_eq_u32 s101, 1
	s_cbranch_scc1 .Lmy_g23_nowb
	buffer_wbl2 sc1
.Lmy_g23_nowb:
	s_nop 0
	s_waitcnt lgkmcnt(0)
	s_waitcnt vmcnt(0)
	v_mbcnt_lo_u32_b32 v3, s12, 0
	v_mbcnt_hi_u32_b32 v3, s13, v3
	v_cmp_eq_u32_e32 vcc, 0, v3
	s_and_saveexec_b64 s[14:15], vcc
	s_cbranch_execz .LBB0_971
	s_bcnt1_i32_b64 s4, s[12:13]
	v_mov_b32_e32 v4, s4
	v_readlane_b32 s4, v253, 42
	v_readlane_b32 s5, v253, 43
	s_nop 4
	global_atomic_add v4, v99, v4, s[4:5] sc0
